# candidate ranking in select rewritten: 64-bit (score,~key) compares, 4 candidates per LDS round trip
# speedup vs baseline: 1.0969x; 1.0494x over previous
; template <int PASS> ...
;     ...
;                 else {
;                     if (bin > b0) { const unsigned pos = atomicAdd(&myctl[fq * 4 + 2], 1u); ((unsigned short*)myhist)[fq * 256 + (pos & 255u)] = (unsigned short)key; }
;                     else if (bin == b0) { const unsigned c = atomicAdd(&myctl[fq * 4 + 3], 1u);
;                         if (c < 128u) { float s = 0.f;
; #pragma unroll
;                             for (int r = 0; r < 4; ++r) s += wv[r] * fmaxf(a0[r], 0.f) + wv[4 + r] * fmaxf(a1[r], 0.f);
;                             s = fminf(fmaxf(s, -3.99f), 3.99f);
;                             mycand[(fq * 128 + c) * 2] = (unsigned)((s + 4.f) * 536870912.f); mycand[(fq * 128 + c) * 2 + 1] = (unsigned)key; } }
.Lp2d_slow0:
	s_mov_b64 exec, s[62:63]
	ds_add_rtn_u32 v200, v115, v212 offset:12
	v_max_f32_e32 v201, 0, v52
	v_max_f32_e32 v202, 0, v48
	v_mul_f32_e32 v201, v110, v201
	v_fmac_f32_e32 v201, v106, v202
	v_add_f32_e32 v203, 0, v201
	v_max_f32_e32 v201, 0, v53
	v_max_f32_e32 v202, 0, v49
	v_mul_f32_e32 v201, v111, v201
	v_fmac_f32_e32 v201, v107, v202
	v_add_f32_e32 v203, v201, v203
	v_max_f32_e32 v201, 0, v54
	v_max_f32_e32 v202, 0, v50
	v_mul_f32_e32 v201, v112, v201
	v_fmac_f32_e32 v201, v108, v202
	v_add_f32_e32 v203, v201, v203
	v_max_f32_e32 v201, 0, v55
	v_max_f32_e32 v202, 0, v51
	v_mul_f32_e32 v201, v113, v201
	v_fmac_f32_e32 v201, v109, v202
	v_add_f32_e32 v203, v201, v203
	v_max_f32_e32 v203, 0xc07f5c29, v203
	v_min_f32_e32 v203, 0x407f5c29, v203
	v_add_f32_e32 v203, 4.0, v203
	v_mul_f32_e32 v203, 0x4e000000, v203
	v_cvt_u32_f32_e32 v199, v203
	v_add_u32_e32 v198, 0, v117
	v_not_b32_e32 v198, v198
	s_waitcnt lgkmcnt(0)
	v_cmp_gt_u32_e32 vcc, s81, v200
	s_and_b64 exec, exec, vcc
	v_lshl_add_u32 v200, v200, 3, v141
	ds_write_b64 v200, v[198:199]
	s_mov_b64 exec, -1
	s_branch .Lp2d_back0
.Lp2d_slow1:
	s_mov_b64 exec, s[62:63]
	ds_add_rtn_u32 v200, v115, v212 offset:12
	v_max_f32_e32 v201, 0, v60
	v_max_f32_e32 v202, 0, v56
	v_mul_f32_e32 v201, v110, v201
	v_fmac_f32_e32 v201, v106, v202
	v_add_f32_e32 v203, 0, v201
	v_max_f32_e32 v201, 0, v61
	v_max_f32_e32 v202, 0, v57
	v_mul_f32_e32 v201, v111, v201
	v_fmac_f32_e32 v201, v107, v202
	v_add_f32_e32 v203, v201, v203
	v_max_f32_e32 v201, 0, v62
	v_max_f32_e32 v202, 0, v58
	v_mul_f32_e32 v201, v112, v201
	v_fmac_f32_e32 v201, v108, v202
	v_add_f32_e32 v203, v201, v203
	v_max_f32_e32 v201, 0, v63
	v_max_f32_e32 v202, 0, v59
	v_mul_f32_e32 v201, v113, v201
	v_fmac_f32_e32 v201, v109, v202
	v_add_f32_e32 v203, v201, v203
	v_max_f32_e32 v203, 0xc07f5c29, v203
	v_min_f32_e32 v203, 0x407f5c29, v203
	v_add_f32_e32 v203, 4.0, v203
	v_mul_f32_e32 v203, 0x4e000000, v203
	v_cvt_u32_f32_e32 v199, v203
	v_add_u32_e32 v198, 16, v117
	v_not_b32_e32 v198, v198
	s_waitcnt lgkmcnt(0)
	v_cmp_gt_u32_e32 vcc, s81, v200
	s_and_b64 exec, exec, vcc
	v_lshl_add_u32 v200, v200, 3, v141
	ds_write_b64 v200, v[198:199]
	s_mov_b64 exec, -1
	s_branch .Lp2d_back1
.Lp2d_slow2:
	s_mov_b64 exec, s[62:63]
	ds_add_rtn_u32 v200, v115, v212 offset:12
	v_max_f32_e32 v201, 0, v68
	v_max_f32_e32 v202, 0, v64
	v_mul_f32_e32 v201, v110, v201
	v_fmac_f32_e32 v201, v106, v202
	v_add_f32_e32 v203, 0, v201
	v_max_f32_e32 v201, 0, v69
	v_max_f32_e32 v202, 0, v65
	v_mul_f32_e32 v201, v111, v201
	v_fmac_f32_e32 v201, v107, v202
	v_add_f32_e32 v203, v201, v203
	v_max_f32_e32 v201, 0, v70
	v_max_f32_e32 v202, 0, v66
	v_mul_f32_e32 v201, v112, v201
	v_fmac_f32_e32 v201, v108, v202
	v_add_f32_e32 v203, v201, v203
	v_max_f32_e32 v201, 0, v71
	v_max_f32_e32 v202, 0, v67
	v_mul_f32_e32 v201, v113, v201
	v_fmac_f32_e32 v201, v109, v202
	v_add_f32_e32 v203, v201, v203
	v_max_f32_e32 v203, 0xc07f5c29, v203
	v_min_f32_e32 v203, 0x407f5c29, v203
	v_add_f32_e32 v203, 4.0, v203
	v_mul_f32_e32 v203, 0x4e000000, v203
	v_cvt_u32_f32_e32 v199, v203
	v_add_u32_e32 v198, 32, v117
	v_not_b32_e32 v198, v198
	s_waitcnt lgkmcnt(0)
	v_cmp_gt_u32_e32 vcc, s81, v200
	s_and_b64 exec, exec, vcc
	v_lshl_add_u32 v200, v200, 3, v141
	ds_write_b64 v200, v[198:199]
	s_mov_b64 exec, -1
	s_branch .Lp2d_back2
.Lp2d_slow3:
	s_mov_b64 exec, s[62:63]
	ds_add_rtn_u32 v200, v115, v212 offset:12
	v_max_f32_e32 v201, 0, v52
	v_max_f32_e32 v202, 0, v48
	v_mul_f32_e32 v201, v110, v201
	v_fmac_f32_e32 v201, v106, v202
	v_add_f32_e32 v203, 0, v201
	v_max_f32_e32 v201, 0, v53
	v_max_f32_e32 v202, 0, v49
	v_mul_f32_e32 v201, v111, v201
	v_fmac_f32_e32 v201, v107, v202
	v_add_f32_e32 v203, v201, v203
	v_max_f32_e32 v201, 0, v54
	v_max_f32_e32 v202, 0, v50
	v_mul_f32_e32 v201, v112, v201
	v_fmac_f32_e32 v201, v108, v202
	v_add_f32_e32 v203, v201, v203
	v_max_f32_e32 v201, 0, v55
	v_max_f32_e32 v202, 0, v51
	v_mul_f32_e32 v201, v113, v201
	v_fmac_f32_e32 v201, v109, v202
	v_add_f32_e32 v203, v201, v203
	v_max_f32_e32 v203, 0xc07f5c29, v203
	v_min_f32_e32 v203, 0x407f5c29, v203
	v_add_f32_e32 v203, 4.0, v203
	v_mul_f32_e32 v203, 0x4e000000, v203
	v_cvt_u32_f32_e32 v199, v203
	v_add_u32_e32 v198, 48, v117
	v_not_b32_e32 v198, v198
	s_waitcnt lgkmcnt(0)
	v_cmp_gt_u32_e32 vcc, s81, v200
	s_and_b64 exec, exec, vcc
	v_lshl_add_u32 v200, v200, 3, v141
	ds_write_b64 v200, v[198:199]
	s_mov_b64 exec, -1
	s_branch .Lp2d_back3
.Lp2d_slow4:
	s_mov_b64 exec, s[62:63]
	ds_add_rtn_u32 v200, v115, v212 offset:12
	v_max_f32_e32 v201, 0, v60
	v_max_f32_e32 v202, 0, v56
	v_mul_f32_e32 v201, v110, v201
	v_fmac_f32_e32 v201, v106, v202
	v_add_f32_e32 v203, 0, v201
	v_max_f32_e32 v201, 0, v61
	v_max_f32_e32 v202, 0, v57
	v_mul_f32_e32 v201, v111, v201
	v_fmac_f32_e32 v201, v107, v202
	v_add_f32_e32 v203, v201, v203
	v_max_f32_e32 v201, 0, v62
	v_max_f32_e32 v202, 0, v58
	v_mul_f32_e32 v201, v112, v201
	v_fmac_f32_e32 v201, v108, v202
	v_add_f32_e32 v203, v201, v203
	v_max_f32_e32 v201, 0, v63
	v_max_f32_e32 v202, 0, v59
	v_mul_f32_e32 v201, v113, v201
	v_fmac_f32_e32 v201, v109, v202
	v_add_f32_e32 v203, v201, v203
	v_max_f32_e32 v203, 0xc07f5c29, v203
	v_min_f32_e32 v203, 0x407f5c29, v203
	v_add_f32_e32 v203, 4.0, v203
	v_mul_f32_e32 v203, 0x4e000000, v203
	v_cvt_u32_f32_e32 v199, v203
	v_add_u32_e32 v198, 64, v117
	v_not_b32_e32 v198, v198
	s_waitcnt lgkmcnt(0)
	v_cmp_gt_u32_e32 vcc, s81, v200
	s_and_b64 exec, exec, vcc
	v_lshl_add_u32 v200, v200, 3, v141
	ds_write_b64 v200, v[198:199]
	s_mov_b64 exec, -1
	s_branch .Lp2d_back4
; template <int PASS> ...
;     ...
;                 else {
;                     if (bin > b0) { const unsigned pos = atomicAdd(&myctl[fq * 4 + 2], 1u); ((unsigned short*)myhist)[fq * 256 + (pos & 255u)] = (unsigned short)key; }
;                     else if (bin == b0) { const unsigned c = atomicAdd(&myctl[fq * 4 + 3], 1u);
;                         if (c < 128u) { float s = 0.f;
; #pragma unroll
;                             for (int r = 0; r < 4; ++r) s += wv[r] * fmaxf(a0[r], 0.f) + wv[4 + r] * fmaxf(a1[r], 0.f);
;                             s = fminf(fmaxf(s, -3.99f), 3.99f);
;                             mycand[(fq * 128 + c) * 2] = (unsigned)((s + 4.f) * 536870912.f); mycand[(fq * 128 + c) * 2 + 1] = (unsigned)key; } }
.Lp2d_slow5:
	s_mov_b64 exec, s[62:63]
	ds_add_rtn_u32 v200, v115, v212 offset:12
	v_max_f32_e32 v201, 0, v68
	v_max_f32_e32 v202, 0, v64
	v_mul_f32_e32 v201, v110, v201
	v_fmac_f32_e32 v201, v106, v202
	v_add_f32_e32 v203, 0, v201
	v_max_f32_e32 v201, 0, v69
	v_max_f32_e32 v202, 0, v65
	v_mul_f32_e32 v201, v111, v201
	v_fmac_f32_e32 v201, v107, v202
	v_add_f32_e32 v203, v201, v203
	v_max_f32_e32 v201, 0, v70
	v_max_f32_e32 v202, 0, v66
	v_mul_f32_e32 v201, v112, v201
	v_fmac_f32_e32 v201, v108, v202
	v_add_f32_e32 v203, v201, v203
	v_max_f32_e32 v201, 0, v71
	v_max_f32_e32 v202, 0, v67
	v_mul_f32_e32 v201, v113, v201
	v_fmac_f32_e32 v201, v109, v202
	v_add_f32_e32 v203, v201, v203
	v_max_f32_e32 v203, 0xc07f5c29, v203
	v_min_f32_e32 v203, 0x407f5c29, v203
	v_add_f32_e32 v203, 4.0, v203
	v_mul_f32_e32 v203, 0x4e000000, v203
	v_cvt_u32_f32_e32 v199, v203
	v_add_u32_e32 v198, 80, v117
	v_not_b32_e32 v198, v198
	s_waitcnt lgkmcnt(0)
	v_cmp_gt_u32_e32 vcc, s81, v200
	s_and_b64 exec, exec, vcc
	v_lshl_add_u32 v200, v200, 3, v141
	ds_write_b64 v200, v[198:199]
	s_mov_b64 exec, -1
	s_branch .Lp2d_back5
.Lp2d_slow6:
	s_mov_b64 exec, s[62:63]
	ds_add_rtn_u32 v200, v115, v212 offset:12
	v_max_f32_e32 v201, 0, v52
	v_max_f32_e32 v202, 0, v48
	v_mul_f32_e32 v201, v110, v201
	v_fmac_f32_e32 v201, v106, v202
	v_add_f32_e32 v203, 0, v201
	v_max_f32_e32 v201, 0, v53
	v_max_f32_e32 v202, 0, v49
	v_mul_f32_e32 v201, v111, v201
	v_fmac_f32_e32 v201, v107, v202
	v_add_f32_e32 v203, v201, v203
	v_max_f32_e32 v201, 0, v54
	v_max_f32_e32 v202, 0, v50
	v_mul_f32_e32 v201, v112, v201
	v_fmac_f32_e32 v201, v108, v202
	v_add_f32_e32 v203, v201, v203
	v_max_f32_e32 v201, 0, v55
	v_max_f32_e32 v202, 0, v51
	v_mul_f32_e32 v201, v113, v201
	v_fmac_f32_e32 v201, v109, v202
	v_add_f32_e32 v203, v201, v203
	v_max_f32_e32 v203, 0xc07f5c29, v203
	v_min_f32_e32 v203, 0x407f5c29, v203
	v_add_f32_e32 v203, 4.0, v203
	v_mul_f32_e32 v203, 0x4e000000, v203
	v_cvt_u32_f32_e32 v199, v203
	v_add_u32_e32 v198, 96, v117
	v_not_b32_e32 v198, v198
	s_waitcnt lgkmcnt(0)
	v_cmp_gt_u32_e32 vcc, s81, v200
	s_and_b64 exec, exec, vcc
	v_lshl_add_u32 v200, v200, 3, v141
	ds_write_b64 v200, v[198:199]
	s_mov_b64 exec, -1
	s_branch .Lp2d_back6
.Lp2d_slow7:
	s_mov_b64 exec, s[62:63]
	ds_add_rtn_u32 v200, v115, v212 offset:12
	v_max_f32_e32 v201, 0, v60
	v_max_f32_e32 v202, 0, v56
	v_mul_f32_e32 v201, v110, v201
	v_fmac_f32_e32 v201, v106, v202
	v_add_f32_e32 v203, 0, v201
	v_max_f32_e32 v201, 0, v61
	v_max_f32_e32 v202, 0, v57
	v_mul_f32_e32 v201, v111, v201
	v_fmac_f32_e32 v201, v107, v202
	v_add_f32_e32 v203, v201, v203
	v_max_f32_e32 v201, 0, v62
	v_max_f32_e32 v202, 0, v58
	v_mul_f32_e32 v201, v112, v201
	v_fmac_f32_e32 v201, v108, v202
	v_add_f32_e32 v203, v201, v203
	v_max_f32_e32 v201, 0, v63
	v_max_f32_e32 v202, 0, v59
	v_mul_f32_e32 v201, v113, v201
	v_fmac_f32_e32 v201, v109, v202
	v_add_f32_e32 v203, v201, v203
	v_max_f32_e32 v203, 0xc07f5c29, v203
	v_min_f32_e32 v203, 0x407f5c29, v203
	v_add_f32_e32 v203, 4.0, v203
	v_mul_f32_e32 v203, 0x4e000000, v203
	v_cvt_u32_f32_e32 v199, v203
	v_add_u32_e32 v198, 112, v117
	v_not_b32_e32 v198, v198
	s_waitcnt lgkmcnt(0)
	v_cmp_gt_u32_e32 vcc, s81, v200
	s_and_b64 exec, exec, vcc
	v_lshl_add_u32 v200, v200, 3, v141
	ds_write_b64 v200, v[198:199]
	s_mov_b64 exec, -1
	s_branch .Lp2d_back7
.Lp2d_slow8:
	s_mov_b64 exec, s[62:63]
	ds_add_rtn_u32 v200, v115, v212 offset:12
	v_max_f32_e32 v201, 0, v68
	v_max_f32_e32 v202, 0, v64
	v_mul_f32_e32 v201, v110, v201
	v_fmac_f32_e32 v201, v106, v202
	v_add_f32_e32 v203, 0, v201
	v_max_f32_e32 v201, 0, v69
	v_max_f32_e32 v202, 0, v65
	v_mul_f32_e32 v201, v111, v201
	v_fmac_f32_e32 v201, v107, v202
	v_add_f32_e32 v203, v201, v203
	v_max_f32_e32 v201, 0, v70
	v_max_f32_e32 v202, 0, v66
	v_mul_f32_e32 v201, v112, v201
	v_fmac_f32_e32 v201, v108, v202
	v_add_f32_e32 v203, v201, v203
	v_max_f32_e32 v201, 0, v71
	v_max_f32_e32 v202, 0, v67
	v_mul_f32_e32 v201, v113, v201
	v_fmac_f32_e32 v201, v109, v202
	v_add_f32_e32 v203, v201, v203
	v_max_f32_e32 v203, 0xc07f5c29, v203
	v_min_f32_e32 v203, 0x407f5c29, v203
	v_add_f32_e32 v203, 4.0, v203
	v_mul_f32_e32 v203, 0x4e000000, v203
	v_cvt_u32_f32_e32 v199, v203
	v_add_u32_e32 v198, 128, v117
	v_not_b32_e32 v198, v198
	s_waitcnt lgkmcnt(0)
	v_cmp_gt_u32_e32 vcc, s81, v200
	s_and_b64 exec, exec, vcc
	v_lshl_add_u32 v200, v200, 3, v141
	ds_write_b64 v200, v[198:199]
	s_mov_b64 exec, -1
	s_branch .Lp2d_back8
.Lp2d_slow9:
	s_mov_b64 exec, s[62:63]
	ds_add_rtn_u32 v200, v115, v212 offset:12
	v_max_f32_e32 v201, 0, v52
	v_max_f32_e32 v202, 0, v48
	v_mul_f32_e32 v201, v110, v201
	v_fmac_f32_e32 v201, v106, v202
	v_add_f32_e32 v203, 0, v201
	v_max_f32_e32 v201, 0, v53
	v_max_f32_e32 v202, 0, v49
	v_mul_f32_e32 v201, v111, v201
	v_fmac_f32_e32 v201, v107, v202
	v_add_f32_e32 v203, v201, v203
	v_max_f32_e32 v201, 0, v54
	v_max_f32_e32 v202, 0, v50
	v_mul_f32_e32 v201, v112, v201
	v_fmac_f32_e32 v201, v108, v202
	v_add_f32_e32 v203, v201, v203
	v_max_f32_e32 v201, 0, v55
	v_max_f32_e32 v202, 0, v51
	v_mul_f32_e32 v201, v113, v201
	v_fmac_f32_e32 v201, v109, v202
	v_add_f32_e32 v203, v201, v203
	v_max_f32_e32 v203, 0xc07f5c29, v203
	v_min_f32_e32 v203, 0x407f5c29, v203
	v_add_f32_e32 v203, 4.0, v203
	v_mul_f32_e32 v203, 0x4e000000, v203
	v_cvt_u32_f32_e32 v199, v203
	v_add_u32_e32 v198, 144, v117
	v_not_b32_e32 v198, v198
	s_waitcnt lgkmcnt(0)
	v_cmp_gt_u32_e32 vcc, s81, v200
	s_and_b64 exec, exec, vcc
	v_lshl_add_u32 v200, v200, 3, v141
	ds_write_b64 v200, v[198:199]
	s_mov_b64 exec, -1
	s_branch .Lp2d_back9
; template <int PASS> ...
;     ...
;                 else {
;                     if (bin > b0) { const unsigned pos = atomicAdd(&myctl[fq * 4 + 2], 1u); ((unsigned short*)myhist)[fq * 256 + (pos & 255u)] = (unsigned short)key; }
;                     else if (bin == b0) { const unsigned c = atomicAdd(&myctl[fq * 4 + 3], 1u);
;                         if (c < 128u) { float s = 0.f;
; #pragma unroll
;                             for (int r = 0; r < 4; ++r) s += wv[r] * fmaxf(a0[r], 0.f) + wv[4 + r] * fmaxf(a1[r], 0.f);
;                             s = fminf(fmaxf(s, -3.99f), 3.99f);
;                             mycand[(fq * 128 + c) * 2] = (unsigned)((s + 4.f) * 536870912.f); mycand[(fq * 128 + c) * 2 + 1] = (unsigned)key; } }
.Lp2d_slow10:
	s_mov_b64 exec, s[62:63]
	ds_add_rtn_u32 v200, v115, v212 offset:12
	v_max_f32_e32 v201, 0, v60
	v_max_f32_e32 v202, 0, v56
	v_mul_f32_e32 v201, v110, v201
	v_fmac_f32_e32 v201, v106, v202
	v_add_f32_e32 v203, 0, v201
	v_max_f32_e32 v201, 0, v61
	v_max_f32_e32 v202, 0, v57
	v_mul_f32_e32 v201, v111, v201
	v_fmac_f32_e32 v201, v107, v202
	v_add_f32_e32 v203, v201, v203
	v_max_f32_e32 v201, 0, v62
	v_max_f32_e32 v202, 0, v58
	v_mul_f32_e32 v201, v112, v201
	v_fmac_f32_e32 v201, v108, v202
	v_add_f32_e32 v203, v201, v203
	v_max_f32_e32 v201, 0, v63
	v_max_f32_e32 v202, 0, v59
	v_mul_f32_e32 v201, v113, v201
	v_fmac_f32_e32 v201, v109, v202
	v_add_f32_e32 v203, v201, v203
	v_max_f32_e32 v203, 0xc07f5c29, v203
	v_min_f32_e32 v203, 0x407f5c29, v203
	v_add_f32_e32 v203, 4.0, v203
	v_mul_f32_e32 v203, 0x4e000000, v203
	v_cvt_u32_f32_e32 v199, v203
	v_add_u32_e32 v198, 160, v117
	v_not_b32_e32 v198, v198
	s_waitcnt lgkmcnt(0)
	v_cmp_gt_u32_e32 vcc, s81, v200
	s_and_b64 exec, exec, vcc
	v_lshl_add_u32 v200, v200, 3, v141
	ds_write_b64 v200, v[198:199]
	s_mov_b64 exec, -1
	s_branch .Lp2d_back10
.Lp2d_slow11:
	s_mov_b64 exec, s[62:63]
	ds_add_rtn_u32 v200, v115, v212 offset:12
	v_max_f32_e32 v201, 0, v68
	v_max_f32_e32 v202, 0, v64
	v_mul_f32_e32 v201, v110, v201
	v_fmac_f32_e32 v201, v106, v202
	v_add_f32_e32 v203, 0, v201
	v_max_f32_e32 v201, 0, v69
	v_max_f32_e32 v202, 0, v65
	v_mul_f32_e32 v201, v111, v201
	v_fmac_f32_e32 v201, v107, v202
	v_add_f32_e32 v203, v201, v203
	v_max_f32_e32 v201, 0, v70
	v_max_f32_e32 v202, 0, v66
	v_mul_f32_e32 v201, v112, v201
	v_fmac_f32_e32 v201, v108, v202
	v_add_f32_e32 v203, v201, v203
	v_max_f32_e32 v201, 0, v71
	v_max_f32_e32 v202, 0, v67
	v_mul_f32_e32 v201, v113, v201
	v_fmac_f32_e32 v201, v109, v202
	v_add_f32_e32 v203, v201, v203
	v_max_f32_e32 v203, 0xc07f5c29, v203
	v_min_f32_e32 v203, 0x407f5c29, v203
	v_add_f32_e32 v203, 4.0, v203
	v_mul_f32_e32 v203, 0x4e000000, v203
	v_cvt_u32_f32_e32 v199, v203
	v_add_u32_e32 v198, 176, v117
	v_not_b32_e32 v198, v198
	s_waitcnt lgkmcnt(0)
	v_cmp_gt_u32_e32 vcc, s81, v200
	s_and_b64 exec, exec, vcc
	v_lshl_add_u32 v200, v200, 3, v141
	ds_write_b64 v200, v[198:199]
	s_mov_b64 exec, -1
	s_branch .Lp2d_back11
.Lp2d_slow12:
	s_mov_b64 exec, s[62:63]
	ds_add_rtn_u32 v200, v115, v212 offset:12
	v_max_f32_e32 v201, 0, v52
	v_max_f32_e32 v202, 0, v48
	v_mul_f32_e32 v201, v110, v201
	v_fmac_f32_e32 v201, v106, v202
	v_add_f32_e32 v203, 0, v201
	v_max_f32_e32 v201, 0, v53
	v_max_f32_e32 v202, 0, v49
	v_mul_f32_e32 v201, v111, v201
	v_fmac_f32_e32 v201, v107, v202
	v_add_f32_e32 v203, v201, v203
	v_max_f32_e32 v201, 0, v54
	v_max_f32_e32 v202, 0, v50
	v_mul_f32_e32 v201, v112, v201
	v_fmac_f32_e32 v201, v108, v202
	v_add_f32_e32 v203, v201, v203
	v_max_f32_e32 v201, 0, v55
	v_max_f32_e32 v202, 0, v51
	v_mul_f32_e32 v201, v113, v201
	v_fmac_f32_e32 v201, v109, v202
	v_add_f32_e32 v203, v201, v203
	v_max_f32_e32 v203, 0xc07f5c29, v203
	v_min_f32_e32 v203, 0x407f5c29, v203
	v_add_f32_e32 v203, 4.0, v203
	v_mul_f32_e32 v203, 0x4e000000, v203
	v_cvt_u32_f32_e32 v199, v203
	v_add_u32_e32 v198, 192, v117
	v_not_b32_e32 v198, v198
	s_waitcnt lgkmcnt(0)
	v_cmp_gt_u32_e32 vcc, s81, v200
	s_and_b64 exec, exec, vcc
	v_lshl_add_u32 v200, v200, 3, v141
	ds_write_b64 v200, v[198:199]
	s_mov_b64 exec, -1
	s_branch .Lp2d_back12
.Lp2d_slow13:
	s_mov_b64 exec, s[62:63]
	ds_add_rtn_u32 v200, v115, v212 offset:12
	v_max_f32_e32 v201, 0, v60
	v_max_f32_e32 v202, 0, v56
	v_mul_f32_e32 v201, v110, v201
	v_fmac_f32_e32 v201, v106, v202
	v_add_f32_e32 v203, 0, v201
	v_max_f32_e32 v201, 0, v61
	v_max_f32_e32 v202, 0, v57
	v_mul_f32_e32 v201, v111, v201
	v_fmac_f32_e32 v201, v107, v202
	v_add_f32_e32 v203, v201, v203
	v_max_f32_e32 v201, 0, v62
	v_max_f32_e32 v202, 0, v58
	v_mul_f32_e32 v201, v112, v201
	v_fmac_f32_e32 v201, v108, v202
	v_add_f32_e32 v203, v201, v203
	v_max_f32_e32 v201, 0, v63
	v_max_f32_e32 v202, 0, v59
	v_mul_f32_e32 v201, v113, v201
	v_fmac_f32_e32 v201, v109, v202
	v_add_f32_e32 v203, v201, v203
	v_max_f32_e32 v203, 0xc07f5c29, v203
	v_min_f32_e32 v203, 0x407f5c29, v203
	v_add_f32_e32 v203, 4.0, v203
	v_mul_f32_e32 v203, 0x4e000000, v203
	v_cvt_u32_f32_e32 v199, v203
	v_add_u32_e32 v198, 208, v117
	v_not_b32_e32 v198, v198
	s_waitcnt lgkmcnt(0)
	v_cmp_gt_u32_e32 vcc, s81, v200
	s_and_b64 exec, exec, vcc
	v_lshl_add_u32 v200, v200, 3, v141
	ds_write_b64 v200, v[198:199]
	s_mov_b64 exec, -1
	s_branch .Lp2d_back13
.Lp2d_slow14:
	s_mov_b64 exec, s[62:63]
	ds_add_rtn_u32 v200, v115, v212 offset:12
	v_max_f32_e32 v201, 0, v68
	v_max_f32_e32 v202, 0, v64
	v_mul_f32_e32 v201, v110, v201
	v_fmac_f32_e32 v201, v106, v202
	v_add_f32_e32 v203, 0, v201
	v_max_f32_e32 v201, 0, v69
	v_max_f32_e32 v202, 0, v65
	v_mul_f32_e32 v201, v111, v201
	v_fmac_f32_e32 v201, v107, v202
	v_add_f32_e32 v203, v201, v203
	v_max_f32_e32 v201, 0, v70
	v_max_f32_e32 v202, 0, v66
	v_mul_f32_e32 v201, v112, v201
	v_fmac_f32_e32 v201, v108, v202
	v_add_f32_e32 v203, v201, v203
	v_max_f32_e32 v201, 0, v71
	v_max_f32_e32 v202, 0, v67
	v_mul_f32_e32 v201, v113, v201
	v_fmac_f32_e32 v201, v109, v202
	v_add_f32_e32 v203, v201, v203
	v_max_f32_e32 v203, 0xc07f5c29, v203
	v_min_f32_e32 v203, 0x407f5c29, v203
	v_add_f32_e32 v203, 4.0, v203
	v_mul_f32_e32 v203, 0x4e000000, v203
	v_cvt_u32_f32_e32 v199, v203
	v_add_u32_e32 v198, 224, v117
	v_not_b32_e32 v198, v198
	s_waitcnt lgkmcnt(0)
	v_cmp_gt_u32_e32 vcc, s81, v200
	s_and_b64 exec, exec, vcc
	v_lshl_add_u32 v200, v200, 3, v141
	ds_write_b64 v200, v[198:199]
	s_mov_b64 exec, -1
	s_branch .Lp2d_back14
.Lp2d_slow15:
	s_mov_b64 exec, s[62:63]
	ds_add_rtn_u32 v200, v115, v212 offset:12
	v_max_f32_e32 v201, 0, v52
	v_max_f32_e32 v202, 0, v48
	v_mul_f32_e32 v201, v110, v201
	v_fmac_f32_e32 v201, v106, v202
	v_add_f32_e32 v203, 0, v201
	v_max_f32_e32 v201, 0, v53
	v_max_f32_e32 v202, 0, v49
	v_mul_f32_e32 v201, v111, v201
	v_fmac_f32_e32 v201, v107, v202
	v_add_f32_e32 v203, v201, v203
	v_max_f32_e32 v201, 0, v54
	v_max_f32_e32 v202, 0, v50
	v_mul_f32_e32 v201, v112, v201
	v_fmac_f32_e32 v201, v108, v202
	v_add_f32_e32 v203, v201, v203
	v_max_f32_e32 v201, 0, v55
	v_max_f32_e32 v202, 0, v51
	v_mul_f32_e32 v201, v113, v201
	v_fmac_f32_e32 v201, v109, v202
	v_add_f32_e32 v203, v201, v203
	v_max_f32_e32 v203, 0xc07f5c29, v203
	v_min_f32_e32 v203, 0x407f5c29, v203
	v_add_f32_e32 v203, 4.0, v203
	v_mul_f32_e32 v203, 0x4e000000, v203
	v_cvt_u32_f32_e32 v199, v203
	v_add_u32_e32 v198, 240, v117
	v_not_b32_e32 v198, v198
	s_waitcnt lgkmcnt(0)
	v_cmp_gt_u32_e32 vcc, s81, v200
	s_and_b64 exec, exec, vcc
	v_lshl_add_u32 v200, v200, 3, v141
	ds_write_b64 v200, v[198:199]
	s_mov_b64 exec, -1
	s_branch .Lp2d_back15

; __device__ __forceinline__ void dsa_select(const h16* PROJ, unsigned short* IDX, int* CNT, unsigned char* shm, unsigned* bar, unsigned xcc, unsigned xrank) {
;     ...
;             { const unsigned nc = myctl[fq * 4 + 3], need = myctl[fq * 4 + 1]; const int n = (int)(nc < 128u ? nc : 128u);
;               for (int ci = fr; ci < n; ci += 16) { const unsigned ki = mycand[(fq * 128 + ci) * 2], ii = mycand[(fq * 128 + ci) * 2 + 1]; unsigned rk = 0u;
;                   for (int jx = 0; jx < n; ++jx) { const unsigned kj = mycand[(fq * 128 + jx) * 2], ij = mycand[(fq * 128 + jx) * 2 + 1]; rk += (kj > ki || (kj == ki && ij < ii)) ? 1u : 0u; }
;                   if (rk < need) { const unsigned pos = atomicAdd(&myctl[fq * 4 + 2], 1u); ((unsigned short*)myhist)[fq * 256 + (pos & 255u)] = (unsigned short)ii; } } }
.LBB0_425:
	ds_read_b32 v0, v115 offset:12
	ds_read_b32 v2, v115 offset:4
	s_waitcnt lgkmcnt(0)
	v_min_u32_e32 v3, 0x80, v0
	v_add_u32_e32 v4, v3, v125
	v_add_u32_e32 v5, 3, v3
	v_and_b32_e32 v5, -4, v5
	v_mov_b32_e32 v8, 0
	v_mov_b32_e32 v9, 0
	v_cmp_lt_u32_e32 vcc, v4, v5
	s_and_saveexec_b64 s[60:61], vcc
	s_cbranch_execz .Lrk_padded
	v_add_u32_e32 v6, v4, v143
	v_lshl_add_u32 v6, v6, 3, v127
	ds_write_b64 v6, v[8:9]
.Lrk_padded:
	s_or_b64 exec, exec, s[60:61]
	s_waitcnt lgkmcnt(0)
	v_cmp_gt_u32_e32 vcc, v3, v125
	s_and_saveexec_b64 s[60:61], vcc
	s_cbranch_execz .LBB0_434
	v_mov_b32_e32 v4, v125
	s_mov_b64 s[62:63], 0
.Lrk_outer:
	v_add_u32_e32 v0, v4, v143
	v_lshl_add_u32 v0, v0, 3, v127
	ds_read_b64 v[0:1], v0
	v_mov_b32_e32 v16, 0
	v_add_u32_e32 v6, -4, v186
	v_mov_b32_e32 v7, v5
	s_mov_b64 s[64:65], 0
.Lrk_inner:
	ds_read_b128 v[8:11], v6
	ds_read_b128 v[12:15], v6 offset:16
	v_add_u32_e32 v6, 32, v6
	v_add_u32_e32 v7, -4, v7
	s_waitcnt lgkmcnt(0)
	v_cmp_gt_u64_e64 s[84:85], v[8:9], v[0:1]
	v_cmp_gt_u64_e64 s[4:5], v[10:11], v[0:1]
	v_cmp_gt_u64_e64 s[58:59], v[12:13], v[0:1]
	v_cmp_gt_u64_e32 vcc, v[14:15], v[0:1]
	s_nop 0
	v_addc_co_u32_e64 v16, s[84:85], 0, v16, s[84:85]
	v_addc_co_u32_e64 v16, s[4:5], 0, v16, s[4:5]
	v_addc_co_u32_e64 v16, s[58:59], 0, v16, s[58:59]
	v_addc_co_u32_e32 v16, vcc, 0, v16, vcc
	v_cmp_eq_u32_e32 vcc, 0, v7
	s_or_b64 s[64:65], vcc, s[64:65]
	s_andn2_b64 exec, exec, s[64:65]
	s_cbranch_execnz .Lrk_inner
	s_mov_b64 exec, s[60:61]
	v_cmp_lt_u32_e32 vcc, v4, v3
	s_and_b64 exec, exec, vcc
	v_cmp_lt_u32_e32 vcc, v16, v2
	s_and_saveexec_b64 s[58:59], vcc
	s_cbranch_execz .Lrk_noemit
	ds_add_rtn_u32 v8, v115, v212 offset:8
	v_not_b32_e32 v9, v0
	s_waitcnt lgkmcnt(0)
	v_and_b32_e32 v8, 0xff, v8
	v_lshl_add_u32 v8, v8, 1, v144
	ds_write_b16 v8, v9
.Lrk_noemit:
	s_or_b64 exec, exec, s[58:59]
	v_add_u32_e32 v4, 16, v4
	v_cmp_ge_u32_e32 vcc, v4, v3
	s_or_b64 s[62:63], vcc, s[62:63]
	s_andn2_b64 exec, exec, s[62:63]
	s_cbranch_execnz .Lrk_outer

; __device__ __forceinline__ void dsa_attend(const h16* PROJ, const unsigned short* IDX, const int* CNT, h16* MIXA, unsigned char* shm, unsigned* bar, unsigned xcc, unsigned xrank) {
;     ...
;             f32x2 oa2[4][8];
; #pragma unroll
;             for (int h = 0; h < 4; ++h)
; #pragma unroll
;                 for (int d = 0; d < 8; ++d) oa2[h][d] = (f32x2){0.f, 0.f};
.LBB0_848:
	s_or_b64 exec, exec, s[50:51]
	s_waitcnt lgkmcnt(0)
	v_mov_b32_e32 v110, 0
	s_mov_b32 s50, 0
	v_mov_b32_e32 v225, v209
	v_mov_b32_e32 v111, v110
	v_mov_b64_e32 v[112:113], 0
	v_mov_b64_e32 v[118:119], 0
	v_mov_b64_e32 v[116:117], 0
	v_mov_b64_e32 v[120:121], 0
	v_mov_b64_e32 v[108:109], 0
	v_mov_b64_e32 v[122:123], 0
	v_mov_b64_e32 v[114:115], 0
	v_mov_b64_e32 v[104:105], 0
	v_mov_b64_e32 v[92:93], 0
	v_mov_b64_e32 v[98:99], 0
	v_mov_b64_e32 v[96:97], 0
	v_mov_b64_e32 v[102:103], 0
	v_mov_b64_e32 v[100:101], 0
	v_mov_b64_e32 v[106:107], 0
	v_mov_b64_e32 v[94:95], 0
	v_mov_b64_e32 v[86:87], 0
	v_mov_b64_e32 v[76:77], 0
	v_mov_b64_e32 v[90:91], 0
	v_mov_b64_e32 v[78:79], 0
	v_mov_b64_e32 v[82:83], 0
	v_mov_b64_e32 v[80:81], 0
	v_mov_b64_e32 v[88:89], 0
	v_mov_b64_e32 v[84:85], 0
	v_mov_b64_e32 v[68:69], 0
	v_mov_b64_e32 v[60:61], 0
	v_mov_b64_e32 v[72:73], 0
	v_mov_b64_e32 v[62:63], 0
	v_mov_b64_e32 v[74:75], 0
	v_mov_b64_e32 v[64:65], 0
	s_waitcnt lgkmcnt(1)
	s_waitcnt lgkmcnt(0)
	v_mov_b64_e32 v[70:71], 0
	v_mov_b64_e32 v[66:67], 0
